# nt also on the P4 state-tile loads and the P2 weight-conversion loads (read-once streams)
# speedup vs baseline: 1.0879x; 1.0072x over previous
.LBB0_1804:
	s_add_i32 s2, s15, 0x100
	s_cmpk_gt_i32 s2, 0xbf
	s_mov_b64 s[4:5], -1
	s_cbranch_scc0 .LBB0_1826
	s_cmpk_gt_u32 s2, 0xff
	s_cbranch_scc0 .LBB0_1823
	v_mov_b32_e32 v23, v0
	s_lshr_b32 s5, s15, 4
	v_and_b32_e32 v17, 63, v23
	v_lshlrev_b32_e32 v2, 2, v17
	v_lshl_add_u64 v[4:5], s[46:47], 0, v[2:3]
	v_add_u32_e32 v2, 0x800, v23
	v_ashrrev_i32_e32 v9, 6, v2
	v_add_u32_e32 v2, 0xa00, v23
	s_lshl_b32 s2, s5, 7
	v_add_u32_e32 v22, 0x200, v23
	v_add_u32_e32 v21, 0x400, v23
	v_ashrrev_i32_e32 v7, 6, v2
	v_add_u32_e32 v2, 0xc00, v23
	s_and_b32 s4, s16, 0x3c0
	v_ashrrev_i32_e32 v43, 6, v23
	v_lshl_add_u64 v[56:57], s[2:3], 2, v[4:5]
	v_ashrrev_i32_e32 v15, 6, v22
	v_ashrrev_i32_e32 v13, 6, v21
	v_add_u32_e32 v20, 0x600, v23
	v_ashrrev_i32_e32 v5, 6, v2
	v_add_u32_e32 v2, 0xe00, v23
	v_add_u32_e32 v18, s4, v43
	v_add_u32_e32 v16, s4, v15
	v_add_u32_e32 v14, s4, v13
	v_ashrrev_i32_e32 v11, 6, v20
	v_add_u32_e32 v10, s4, v9
	v_ashrrev_i32_e32 v24, 6, v2
	v_mad_i64_i32 v[26:27], s[24:25], v18, s20, v[56:57]
	v_mad_i64_i32 v[28:29], s[24:25], v16, s20, v[56:57]
	v_mad_i64_i32 v[30:31], s[24:25], v14, s20, v[56:57]
	v_add_u32_e32 v12, s4, v11
	v_mad_i64_i32 v[36:37], s[24:25], v10, s20, v[56:57]
	v_add_u32_e32 v8, s4, v7
	v_add_u32_e32 v6, s4, v5
	v_add_u32_e32 v4, s4, v24
	v_mad_i64_i32 v[32:33], s[24:25], v12, s20, v[56:57]
	v_mad_i64_i32 v[40:41], s[24:25], v8, s20, v[56:57]
	v_mad_i64_i32 v[54:55], s[24:25], v6, s20, v[56:57]
	v_mad_i64_i32 v[58:59], s[24:25], v4, s20, v[56:57]
	global_load_dword v51, v[26:27], off nt
	global_load_dword v47, v[28:29], off nt
	global_load_dword v42, v[30:31], off nt
	global_load_dword v38, v[32:33], off nt
	global_load_dword v39, v[32:33], off offset:256 nt
	global_load_dword v44, v[30:31], off offset:256 nt
	global_load_dword v48, v[28:29], off offset:256 nt
	global_load_dword v52, v[26:27], off offset:256 nt
	global_load_dword v34, v[36:37], off nt
	s_nop 0
	global_load_dword v30, v[40:41], off nt
	global_load_dword v27, v[54:55], off nt
	global_load_dword v25, v[58:59], off nt
	global_load_dword v26, v[58:59], off offset:256 nt
	global_load_dword v28, v[54:55], off offset:256 nt
	global_load_dword v31, v[40:41], off offset:256 nt
	s_nop 0
	global_load_dword v36, v[36:37], off offset:256 nt
	v_lshl_add_u64 v[32:33], v[56:57], 0, s[6:7]
	v_mad_i64_i32 v[40:41], s[24:25], v18, s20, v[32:33]
	v_mad_i64_i32 v[58:59], s[24:25], v16, s20, v[32:33]
	v_lshl_add_u64 v[56:57], v[56:57], 0, s[8:9]
	v_mad_i64_i32 v[60:61], s[24:25], v14, s20, v[32:33]
	v_mad_i64_i32 v[62:63], s[24:25], v12, s20, v[32:33]
	v_mad_i64_i32 v[64:65], s[24:25], v10, s20, v[32:33]
	v_mad_i64_i32 v[66:67], s[24:25], v8, s20, v[32:33]
	v_mad_i64_i32 v[68:69], s[24:25], v6, s20, v[32:33]
	v_mad_i64_i32 v[70:71], s[24:25], v4, s20, v[32:33]
	global_load_dword v55, v[40:41], off nt
	global_load_dword v53, v[58:59], off nt
	global_load_dword v49, v[60:61], off nt
	global_load_dword v45, v[62:63], off nt
	s_nop 0
	global_load_dword v40, v[64:65], off nt
	global_load_dword v35, v[66:67], off nt
	global_load_dword v32, v[68:69], off nt
	global_load_dword v29, v[70:71], off nt
	v_mad_i64_i32 v[58:59], s[24:25], v18, s20, v[56:57]
	v_mad_i64_i32 v[60:61], s[24:25], v16, s20, v[56:57]
	v_mad_i64_i32 v[62:63], s[24:25], v14, s20, v[56:57]
	v_mad_i64_i32 v[64:65], s[24:25], v12, s20, v[56:57]
	v_mad_i64_i32 v[66:67], s[24:25], v10, s20, v[56:57]
	v_mad_i64_i32 v[68:69], s[24:25], v8, s20, v[56:57]
	v_mad_i64_i32 v[70:71], s[24:25], v6, s20, v[56:57]
	v_mad_i64_i32 v[72:73], s[24:25], v4, s20, v[56:57]
	global_load_dword v58, v[58:59], off nt
	s_nop 0
	global_load_dword v56, v[60:61], off nt
	global_load_dword v54, v[62:63], off nt
	global_load_dword v50, v[64:65], off nt
	global_load_dword v46, v[66:67], off nt
	global_load_dword v41, v[68:69], off nt
	global_load_dword v37, v[70:71], off nt
	global_load_dword v33, v[72:73], off nt
	v_mov_b32_e32 v57, 1.0
	s_and_b64 vcc, exec, s[0:1]
	v_mov_b32_e32 v19, 1.0
	s_cbranch_vccnz .LBB0_1808
	v_ashrrev_i32_e32 v19, 31, v18
	v_lshl_add_u64 v[18:19], v[18:19], 2, s[44:45]
	global_load_dword v19, v[18:19], off nt
.LBB0_1808:
	v_lshl_add_u32 v2, v17, 2, 16
	v_mad_u64_u32 v[60:61], s[24:25], v43, s21, v[2:3]
	s_waitcnt vmcnt(0)
	v_mul_f32_e32 v17, v51, v19
	v_mul_f32_e32 v18, v52, v19
	ds_write2st64_b32 v60, v17, v18 offset1:65
	v_mul_f32_e32 v17, v55, v19
	v_mul_f32_e32 v18, v58, v19
	s_and_b64 vcc, exec, s[0:1]
	ds_write2st64_b32 v60, v17, v18 offset0:130 offset1:195
	s_cbranch_vccnz .LBB0_1810
	v_ashrrev_i32_e32 v17, 31, v16
	v_lshl_add_u64 v[16:17], v[16:17], 2, s[44:45]
	global_load_dword v57, v[16:17], off nt
.LBB0_1810:
	v_mad_u64_u32 v[16:17], s[24:25], v15, s21, v[2:3]
	s_waitcnt vmcnt(0)
	v_mul_f32_e32 v15, v47, v57
	v_mul_f32_e32 v17, v48, v57
	ds_write2st64_b32 v16, v15, v17 offset1:65
	v_mul_f32_e32 v15, v53, v57
	v_mul_f32_e32 v17, v56, v57
	ds_write2st64_b32 v16, v15, v17 offset0:130 offset1:195
	v_mov_b32_e32 v16, 1.0
	s_and_b64 vcc, exec, s[0:1]
	v_mov_b32_e32 v15, 1.0
	s_cbranch_vccnz .LBB0_1812
	v_ashrrev_i32_e32 v15, 31, v14
	v_lshl_add_u64 v[14:15], v[14:15], 2, s[44:45]
	global_load_dword v15, v[14:15], off nt
.LBB0_1812:
	v_mad_u64_u32 v[18:19], s[24:25], v13, s21, v[2:3]
	s_waitcnt vmcnt(0)
	v_mul_f32_e32 v13, v42, v15
	v_mul_f32_e32 v14, v44, v15
	ds_write2st64_b32 v18, v13, v14 offset1:65
	v_mul_f32_e32 v13, v49, v15
	v_mul_f32_e32 v14, v54, v15
	s_and_b64 vcc, exec, s[0:1]
	ds_write2st64_b32 v18, v13, v14 offset0:130 offset1:195
	s_cbranch_vccnz .LBB0_1814
	v_ashrrev_i32_e32 v13, 31, v12
	v_lshl_add_u64 v[12:13], v[12:13], 2, s[44:45]
	global_load_dword v16, v[12:13], off nt
.LBB0_1814:
	v_mad_u64_u32 v[12:13], s[24:25], v11, s21, v[2:3]
	s_waitcnt vmcnt(0)
	v_mul_f32_e32 v11, v38, v16
	v_mul_f32_e32 v13, v39, v16
	ds_write2st64_b32 v12, v11, v13 offset1:65
	v_mul_f32_e32 v11, v45, v16
	v_mul_f32_e32 v13, v50, v16
	ds_write2st64_b32 v12, v11, v13 offset0:130 offset1:195
	v_mov_b32_e32 v12, 1.0
	s_and_b64 vcc, exec, s[0:1]
	v_mov_b32_e32 v11, 1.0
	s_cbranch_vccnz .LBB0_1816
	v_ashrrev_i32_e32 v11, 31, v10
	v_lshl_add_u64 v[10:11], v[10:11], 2, s[44:45]
	global_load_dword v11, v[10:11], off nt
.LBB0_1816:
	v_mad_u64_u32 v[14:15], s[24:25], v9, s21, v[2:3]
	s_waitcnt vmcnt(0)
	v_mul_f32_e32 v9, v34, v11
	v_mul_f32_e32 v10, v36, v11
	ds_write2st64_b32 v14, v9, v10 offset1:65
	v_mul_f32_e32 v9, v40, v11
	v_mul_f32_e32 v10, v46, v11
	s_and_b64 vcc, exec, s[0:1]
	ds_write2st64_b32 v14, v9, v10 offset0:130 offset1:195
	s_cbranch_vccnz .LBB0_1818
	v_ashrrev_i32_e32 v9, 31, v8
	v_lshl_add_u64 v[8:9], v[8:9], 2, s[44:45]
	global_load_dword v12, v[8:9], off nt
.LBB0_1818:
	v_mad_u64_u32 v[8:9], s[24:25], v7, s21, v[2:3]
	s_waitcnt vmcnt(0)
	v_mul_f32_e32 v7, v30, v12
	v_mul_f32_e32 v9, v31, v12
	ds_write2st64_b32 v8, v7, v9 offset1:65
	v_mul_f32_e32 v7, v35, v12
	v_mul_f32_e32 v9, v41, v12
	ds_write2st64_b32 v8, v7, v9 offset0:130 offset1:195
	v_mov_b32_e32 v8, 1.0
	s_and_b64 vcc, exec, s[0:1]
	v_mov_b32_e32 v7, 1.0
	s_cbranch_vccnz .LBB0_1820
	v_ashrrev_i32_e32 v7, 31, v6
	v_lshl_add_u64 v[6:7], v[6:7], 2, s[44:45]
	global_load_dword v7, v[6:7], off nt
.LBB0_1820:
	v_mad_u64_u32 v[10:11], s[24:25], v5, s21, v[2:3]
	s_waitcnt vmcnt(0)
	v_mul_f32_e32 v5, v27, v7
	v_mul_f32_e32 v6, v28, v7
	ds_write2st64_b32 v10, v5, v6 offset1:65
	v_mul_f32_e32 v5, v32, v7
	v_mul_f32_e32 v6, v37, v7
	s_and_b64 vcc, exec, s[0:1]
	ds_write2st64_b32 v10, v5, v6 offset0:130 offset1:195
	s_cbranch_vccnz .LBB0_1822
	v_ashrrev_i32_e32 v5, 31, v4
	v_lshl_add_u64 v[4:5], v[4:5], 2, s[44:45]
	global_load_dword v8, v[4:5], off nt

.LBB0_1823:
	s_and_b64 vcc, exec, s[4:5]
	s_cbranch_vccz .LBB0_1825
	v_mov_b32_e32 v22, v0
	s_and_b32 s5, s16, 0x3c0
	v_add_u32_e32 v24, 0x200, v22
	v_add_u32_e32 v26, 0x400, v22
	v_add_u32_e32 v28, 0x600, v22
	v_add_u32_e32 v14, 0x800, v22
	v_add_u32_e32 v16, 0xa00, v22
	v_lshlrev_b32_e32 v2, 2, v22
	v_ashrrev_i32_e32 v23, 6, v22
	v_ashrrev_i32_e32 v25, 6, v24
	v_ashrrev_i32_e32 v27, 6, v26
	v_ashrrev_i32_e32 v29, 6, v28
	v_ashrrev_i32_e32 v30, 6, v14
	v_ashrrev_i32_e32 v31, 6, v16
	s_and_b32 s4, s18, 0xf00
	v_and_b32_e32 v2, 0xfc, v2
	v_add_u32_e32 v6, s5, v23
	v_add_u32_e32 v8, s5, v25
	v_add_u32_e32 v10, s5, v27
	v_add_u32_e32 v12, s5, v29
	v_add_u32_e32 v14, s5, v30
	v_add_u32_e32 v16, s5, v31
	s_add_i32 s2, s4, 0xfffff400
	v_lshl_add_u64 v[4:5], s[42:43], 0, v[2:3]
	v_ashrrev_i32_e32 v7, 31, v6
	v_ashrrev_i32_e32 v9, 31, v8
	v_ashrrev_i32_e32 v11, 31, v10
	v_ashrrev_i32_e32 v13, 31, v12
	v_ashrrev_i32_e32 v15, 31, v14
	v_ashrrev_i32_e32 v17, 31, v16
	v_add_u32_e32 v18, 0xc00, v22
	v_lshlrev_b64 v[6:7], 12, v[6:7]
	v_lshl_add_u64 v[4:5], s[2:3], 2, v[4:5]
	v_lshlrev_b64 v[8:9], 12, v[8:9]
	v_lshlrev_b64 v[10:11], 12, v[10:11]
	v_lshlrev_b64 v[12:13], 12, v[12:13]
	v_lshlrev_b64 v[14:15], 12, v[14:15]
	v_lshlrev_b64 v[16:17], 12, v[16:17]
	v_ashrrev_i32_e32 v32, 6, v18
	v_add_u32_e32 v20, 0xe00, v22
	v_lshl_add_u64 v[6:7], v[4:5], 0, v[6:7]
	v_lshl_add_u64 v[8:9], v[4:5], 0, v[8:9]
	v_lshl_add_u64 v[10:11], v[4:5], 0, v[10:11]
	v_lshl_add_u64 v[12:13], v[4:5], 0, v[12:13]
	v_lshl_add_u64 v[14:15], v[4:5], 0, v[14:15]
	v_lshl_add_u64 v[16:17], v[4:5], 0, v[16:17]
	v_add_u32_e32 v18, s5, v32
	v_ashrrev_i32_e32 v33, 6, v20
	v_ashrrev_i32_e32 v19, 31, v18
	v_add_u32_e32 v20, s5, v33
	global_load_dword v34, v[6:7], off nt
	global_load_dword v35, v[8:9], off nt
	global_load_dword v36, v[6:7], off offset:256 nt
	global_load_dword v37, v[8:9], off offset:256 nt
	global_load_dword v38, v[6:7], off offset:512 nt
	global_load_dword v39, v[8:9], off offset:512 nt
	s_nop 0
	global_load_dword v8, v[8:9], off offset:768 nt
	s_nop 0
	global_load_dword v6, v[6:7], off offset:768 nt
	s_nop 0
	global_load_dword v7, v[10:11], off nt
	global_load_dword v9, v[12:13], off nt
	global_load_dword v40, v[10:11], off offset:256 nt
	global_load_dword v41, v[12:13], off offset:256 nt
	global_load_dword v42, v[10:11], off offset:512 nt
	global_load_dword v43, v[12:13], off offset:512 nt
	s_nop 0
	global_load_dword v12, v[12:13], off offset:768 nt
	s_nop 0
	global_load_dword v10, v[10:11], off offset:768 nt
	s_nop 0
	global_load_dword v11, v[14:15], off nt
	global_load_dword v13, v[16:17], off nt
	global_load_dword v44, v[14:15], off offset:256 nt
	global_load_dword v45, v[16:17], off offset:256 nt
	global_load_dword v46, v[14:15], off offset:512 nt
	global_load_dword v47, v[16:17], off offset:512 nt
	s_nop 0
	global_load_dword v16, v[16:17], off offset:768 nt
	s_nop 0
	global_load_dword v14, v[14:15], off offset:768 nt
	v_lshlrev_b64 v[18:19], 12, v[18:19]
	v_ashrrev_i32_e32 v21, 31, v20
	v_lshl_add_u64 v[18:19], v[4:5], 0, v[18:19]
	v_lshlrev_b64 v[20:21], 12, v[20:21]
	v_lshl_add_u64 v[4:5], v[4:5], 0, v[20:21]
	global_load_dword v15, v[18:19], off nt
	global_load_dword v17, v[18:19], off offset:256 nt
	global_load_dword v20, v[4:5], off offset:256 nt
	global_load_dword v21, v[18:19], off offset:512 nt
	global_load_dword v48, v[4:5], off offset:512 nt
	global_load_dword v49, v[4:5], off offset:768 nt
	s_nop 0
	global_load_dword v18, v[18:19], off offset:768 nt
	s_nop 0
	global_load_dword v19, v[4:5], off nt
	v_add_u32_e32 v2, 16, v2
	v_mad_u64_u32 v[4:5], s[24:25], v23, s21, v[2:3]
	s_lshl_b32 s5, s5, 1
	s_waitcnt vmcnt(29)
	ds_write2st64_b32 v4, v34, v36 offset1:65
	s_waitcnt vmcnt(24)
	ds_write2st64_b32 v4, v38, v6 offset0:130 offset1:195
	v_mad_u64_u32 v[4:5], s[24:25], v25, s21, v[2:3]
	ds_write2st64_b32 v4, v35, v37 offset1:65
	ds_write2st64_b32 v4, v39, v8 offset0:130 offset1:195
	v_mad_u64_u32 v[4:5], s[24:25], v27, s21, v[2:3]
	s_waitcnt vmcnt(21)
	ds_write2st64_b32 v4, v7, v40 offset1:65
	s_waitcnt vmcnt(16)
	ds_write2st64_b32 v4, v42, v10 offset0:130 offset1:195
	v_mad_u64_u32 v[4:5], s[24:25], v29, s21, v[2:3]
	ds_write2st64_b32 v4, v9, v41 offset1:65
	ds_write2st64_b32 v4, v43, v12 offset0:130 offset1:195
	v_mad_u64_u32 v[4:5], s[24:25], v30, s21, v[2:3]
	s_waitcnt vmcnt(13)
	ds_write2st64_b32 v4, v11, v44 offset1:65
	s_waitcnt vmcnt(8)
	ds_write2st64_b32 v4, v46, v14 offset0:130 offset1:195
	v_mad_u64_u32 v[4:5], s[24:25], v31, s21, v[2:3]
	ds_write2st64_b32 v4, v13, v45 offset1:65
	ds_write2st64_b32 v4, v47, v16 offset0:130 offset1:195
	v_mad_u64_u32 v[4:5], s[24:25], v32, s21, v[2:3]
	s_waitcnt vmcnt(6)
	ds_write2st64_b32 v4, v15, v17 offset1:65
	s_waitcnt vmcnt(1)
	ds_write2st64_b32 v4, v21, v18 offset0:130 offset1:195
	v_mad_u64_u32 v[4:5], s[24:25], v33, s21, v[2:3]
	v_lshlrev_b32_e32 v2, 1, v22
	v_and_b32_e32 v2, 62, v2
	v_mad_u32_u24 v10, v2, s21, 16
	v_ashrrev_i32_e32 v11, 5, v22
	v_lshl_add_u32 v12, v11, 2, v10
	s_add_u32 s24, s13, s5
	s_waitcnt vmcnt(0)
	ds_write2st64_b32 v4, v19, v20 offset1:65
	ds_write2st64_b32 v4, v48, v49 offset0:130 offset1:195
	s_waitcnt lgkmcnt(0)
	s_barrier
	ds_read2_b32 v[6:7], v12 offset1:65
	s_addc_u32 s25, s14, 0
	v_lshlrev_b32_e32 v2, 1, v2
	v_lshl_add_u64 v[4:5], s[24:25], 0, v[2:3]
	s_waitcnt lgkmcnt(0)
	v_cvt_pk_bf16_f32 v2, v6, v7
	v_add_u32_e32 v6, s2, v11
	v_ashrrev_i32_e32 v7, 31, v6
	v_lshlrev_b64 v[6:7], 11, v[6:7]
	v_ashrrev_i32_e32 v13, 5, v24
	v_lshl_add_u64 v[6:7], v[4:5], 0, v[6:7]
	global_store_dword v[6:7], v2, off
	v_add_u32_e32 v6, s2, v13
	v_ashrrev_i32_e32 v7, 31, v6
	v_lshlrev_b64 v[6:7], 11, v[6:7]
	v_lshl_add_u32 v14, v13, 2, v10
	v_ashrrev_i32_e32 v15, 5, v26
	v_lshl_add_u64 v[6:7], v[4:5], 0, v[6:7]
	ds_read2_b32 v[8:9], v14 offset1:65
	s_waitcnt lgkmcnt(0)
	v_cvt_pk_bf16_f32 v2, v8, v9
	global_store_dword v[6:7], v2, off
	v_add_u32_e32 v6, s2, v15
	v_ashrrev_i32_e32 v7, 31, v6
	v_lshlrev_b64 v[6:7], 11, v[6:7]
	v_lshl_add_u32 v16, v15, 2, v10
	v_ashrrev_i32_e32 v17, 5, v28
	v_lshl_add_u64 v[6:7], v[4:5], 0, v[6:7]
	ds_read2_b32 v[8:9], v16 offset1:65
	s_waitcnt lgkmcnt(0)
	v_cvt_pk_bf16_f32 v2, v8, v9
	global_store_dword v[6:7], v2, off
	v_add_u32_e32 v6, s2, v17
	v_lshl_add_u32 v10, v17, 2, v10
	v_ashrrev_i32_e32 v7, 31, v6
	ds_read2_b32 v[8:9], v10 offset1:65
	v_lshlrev_b64 v[6:7], 11, v[6:7]
	s_waitcnt lgkmcnt(0)
	v_cvt_pk_bf16_f32 v2, v8, v9
	v_add_u32_e32 v8, 0x4000, v12
	v_lshl_add_u64 v[6:7], v[4:5], 0, v[6:7]
	s_add_i32 s2, s4, 0xfffff440
	ds_read2_b32 v[8:9], v8 offset0:64 offset1:129
	global_store_dword v[6:7], v2, off
	v_add_u32_e32 v6, s2, v11
	v_add_u32_e32 v7, 0x4000, v14
	s_waitcnt lgkmcnt(0)
	v_cvt_pk_bf16_f32 v2, v8, v9
	ds_read2_b32 v[8:9], v7 offset0:64 offset1:129
	v_ashrrev_i32_e32 v7, 31, v6
	v_lshlrev_b64 v[6:7], 11, v[6:7]
	v_lshl_add_u64 v[6:7], v[4:5], 0, v[6:7]
	global_store_dword v[6:7], v2, off
	v_add_u32_e32 v6, s2, v13
	v_add_u32_e32 v7, 0x4000, v16
	s_waitcnt lgkmcnt(0)
	v_cvt_pk_bf16_f32 v2, v8, v9
	ds_read2_b32 v[8:9], v7 offset0:64 offset1:129
	v_ashrrev_i32_e32 v7, 31, v6
	v_lshlrev_b64 v[6:7], 11, v[6:7]
	v_lshl_add_u64 v[6:7], v[4:5], 0, v[6:7]
	global_store_dword v[6:7], v2, off
	v_add_u32_e32 v6, s2, v15
	v_add_u32_e32 v7, 0x4000, v10
	s_waitcnt lgkmcnt(0)
	v_cvt_pk_bf16_f32 v2, v8, v9
	ds_read2_b32 v[8:9], v7 offset0:64 offset1:129
	v_ashrrev_i32_e32 v7, 31, v6
	v_lshlrev_b64 v[6:7], 11, v[6:7]
	v_lshl_add_u64 v[6:7], v[4:5], 0, v[6:7]
	global_store_dword v[6:7], v2, off
	v_add_u32_e32 v6, s2, v17
	v_ashrrev_i32_e32 v7, 31, v6
	v_lshlrev_b64 v[6:7], 11, v[6:7]
	s_waitcnt lgkmcnt(0)
	v_cvt_pk_bf16_f32 v2, v8, v9
	v_add_u32_e32 v8, 0x8000, v12
	v_lshl_add_u64 v[6:7], v[4:5], 0, v[6:7]
	s_add_i32 s2, s4, 0xfffff480
	ds_read2_b32 v[8:9], v8 offset0:128 offset1:193
	global_store_dword v[6:7], v2, off
	v_add_u32_e32 v6, s2, v11
	v_add_u32_e32 v7, 0x8000, v14
	s_waitcnt lgkmcnt(0)
	v_cvt_pk_bf16_f32 v2, v8, v9
	ds_read2_b32 v[8:9], v7 offset0:128 offset1:193
	v_ashrrev_i32_e32 v7, 31, v6
	v_lshlrev_b64 v[6:7], 11, v[6:7]
	v_lshl_add_u64 v[6:7], v[4:5], 0, v[6:7]
	global_store_dword v[6:7], v2, off
	v_add_u32_e32 v6, s2, v13
	v_add_u32_e32 v7, 0x8000, v16
	s_waitcnt lgkmcnt(0)
	v_cvt_pk_bf16_f32 v2, v8, v9
	ds_read2_b32 v[8:9], v7 offset0:128 offset1:193
	v_ashrrev_i32_e32 v7, 31, v6
	v_lshlrev_b64 v[6:7], 11, v[6:7]
	v_lshl_add_u64 v[6:7], v[4:5], 0, v[6:7]
	global_store_dword v[6:7], v2, off
	v_add_u32_e32 v6, s2, v15
	v_add_u32_e32 v7, 0x8000, v10
	s_waitcnt lgkmcnt(0)
	v_cvt_pk_bf16_f32 v2, v8, v9
	ds_read2_b32 v[8:9], v7 offset0:128 offset1:193
	v_ashrrev_i32_e32 v7, 31, v6
	v_lshlrev_b64 v[6:7], 11, v[6:7]
	v_lshl_add_u64 v[6:7], v[4:5], 0, v[6:7]
	global_store_dword v[6:7], v2, off
	v_add_u32_e32 v6, s2, v17
	v_ashrrev_i32_e32 v7, 31, v6
	v_lshlrev_b64 v[6:7], 11, v[6:7]
	s_waitcnt lgkmcnt(0)
	v_cvt_pk_bf16_f32 v2, v8, v9
	v_add_u32_e32 v8, 0xc200, v12
	v_lshl_add_u64 v[6:7], v[4:5], 0, v[6:7]
	s_addk_i32 s4, 0xf4c0
	ds_read2_b32 v[8:9], v8 offset0:64 offset1:129
	global_store_dword v[6:7], v2, off
	v_add_u32_e32 v6, s4, v11
	v_add_u32_e32 v7, 0xc200, v14
	s_waitcnt lgkmcnt(0)
	v_cvt_pk_bf16_f32 v2, v8, v9
	ds_read2_b32 v[8:9], v7 offset0:64 offset1:129
	v_ashrrev_i32_e32 v7, 31, v6
	v_lshlrev_b64 v[6:7], 11, v[6:7]
	v_lshl_add_u64 v[6:7], v[4:5], 0, v[6:7]
	global_store_dword v[6:7], v2, off
	v_add_u32_e32 v6, s4, v13
	v_add_u32_e32 v7, 0xc200, v16
	s_waitcnt lgkmcnt(0)
	v_cvt_pk_bf16_f32 v2, v8, v9
	ds_read2_b32 v[8:9], v7 offset0:64 offset1:129
	v_ashrrev_i32_e32 v7, 31, v6
	v_lshlrev_b64 v[6:7], 11, v[6:7]
	v_lshl_add_u64 v[6:7], v[4:5], 0, v[6:7]
	global_store_dword v[6:7], v2, off
	v_add_u32_e32 v6, s4, v15
	v_add_u32_e32 v7, 0xc200, v10
	s_waitcnt lgkmcnt(0)
	v_cvt_pk_bf16_f32 v2, v8, v9
	ds_read2_b32 v[8:9], v7 offset0:64 offset1:129
	v_ashrrev_i32_e32 v7, 31, v6
	v_lshlrev_b64 v[6:7], 11, v[6:7]
	v_lshl_add_u64 v[6:7], v[4:5], 0, v[6:7]
	global_store_dword v[6:7], v2, off
	v_add_u32_e32 v6, s4, v17
	v_ashrrev_i32_e32 v7, 31, v6
	v_lshlrev_b64 v[6:7], 11, v[6:7]
	v_lshl_add_u64 v[4:5], v[4:5], 0, v[6:7]
	s_waitcnt lgkmcnt(0)
	v_cvt_pk_bf16_f32 v2, v8, v9
	global_store_dword v[4:5], v2, off
	s_barrier

.LBB0_1826:
	s_andn2_b64 vcc, exec, s[4:5]
	s_cbranch_vccnz .LBB0_1803
	s_and_b32 s2, s18, 0xffffff00
	s_or_b32 s4, s2, 8
	v_mov_b32_e32 v20, v0
	s_cmpk_lt_i32 s2, 0x600
	v_readlane_b32 s60, v254, 4
	v_lshlrev_b32_e32 v2, 2, v20
	s_cselect_b32 s4, s2, s4
	v_and_b32_e32 v2, 0xfc, v2
	v_readlane_b32 s62, v254, 6
	v_readlane_b32 s63, v254, 7
	v_add_u32_e32 v22, 0x200, v20
	v_add_u32_e32 v24, 0x400, v20
	v_add_u32_e32 v26, 0x600, v20
	v_add_u32_e32 v14, 0x800, v20
	v_add_u32_e32 v16, 0xa00, v20
	s_and_b32 s23, s16, 0x3c0
	v_lshl_add_u64 v[4:5], s[62:63], 0, v[2:3]
	v_ashrrev_i32_e32 v21, 6, v20
	s_ashr_i32 s5, s4, 31
	v_ashrrev_i32_e32 v23, 6, v22
	v_ashrrev_i32_e32 v25, 6, v24
	v_ashrrev_i32_e32 v27, 6, v26
	v_ashrrev_i32_e32 v28, 6, v14
	v_ashrrev_i32_e32 v29, 6, v16
	v_add_u32_e32 v6, s23, v21
	v_lshl_add_u64 v[4:5], s[4:5], 2, v[4:5]
	v_add_u32_e32 v8, s23, v23
	v_add_u32_e32 v10, s23, v25
	v_add_u32_e32 v12, s23, v27
	v_add_u32_e32 v14, s23, v28
	v_add_u32_e32 v16, s23, v29
	v_mad_i64_i32 v[6:7], s[4:5], v6, s22, v[4:5]
	v_mad_i64_i32 v[8:9], s[4:5], v8, s22, v[4:5]
	v_mad_i64_i32 v[10:11], s[4:5], v10, s22, v[4:5]
	v_mad_i64_i32 v[12:13], s[4:5], v12, s22, v[4:5]
	v_mad_i64_i32 v[14:15], s[4:5], v14, s22, v[4:5]
	v_mad_i64_i32 v[16:17], s[4:5], v16, s22, v[4:5]
	v_add_u32_e32 v18, 0xc00, v20
	v_ashrrev_i32_e32 v30, 6, v18
	v_add_u32_e32 v31, 0xe00, v20
	global_load_dword v33, v[6:7], off nt
	global_load_dword v34, v[8:9], off nt
	global_load_dword v35, v[6:7], off offset:256 nt
	global_load_dword v36, v[8:9], off offset:256 nt
	global_load_dword v37, v[6:7], off offset:512 nt
	global_load_dword v38, v[8:9], off offset:512 nt
	s_nop 0
	global_load_dword v8, v[8:9], off offset:768 nt
	s_nop 0
	global_load_dword v6, v[6:7], off offset:768 nt
	s_nop 0
	global_load_dword v7, v[10:11], off nt
	global_load_dword v9, v[12:13], off nt
	global_load_dword v39, v[10:11], off offset:256 nt
	global_load_dword v40, v[12:13], off offset:256 nt
	global_load_dword v41, v[10:11], off offset:512 nt
	global_load_dword v42, v[12:13], off offset:512 nt
	s_nop 0
	global_load_dword v12, v[12:13], off offset:768 nt
	s_nop 0
	global_load_dword v10, v[10:11], off offset:768 nt
	s_nop 0
	global_load_dword v11, v[14:15], off nt
	global_load_dword v13, v[16:17], off nt
	global_load_dword v43, v[14:15], off offset:256 nt
	global_load_dword v44, v[16:17], off offset:256 nt
	global_load_dword v45, v[14:15], off offset:512 nt
	global_load_dword v46, v[16:17], off offset:512 nt
	s_nop 0
	global_load_dword v16, v[16:17], off offset:768 nt
	s_nop 0
	global_load_dword v14, v[14:15], off offset:768 nt
	v_add_u32_e32 v18, s23, v30
	v_ashrrev_i32_e32 v31, 6, v31
	v_mad_i64_i32 v[18:19], s[4:5], v18, s22, v[4:5]
	v_add_u32_e32 v32, s23, v31
	v_mad_i64_i32 v[4:5], s[4:5], v32, s22, v[4:5]
	global_load_dword v15, v[18:19], off nt
	global_load_dword v17, v[18:19], off offset:256 nt
	global_load_dword v32, v[4:5], off offset:256 nt
	global_load_dword v47, v[18:19], off offset:512 nt
	global_load_dword v48, v[4:5], off offset:512 nt
	global_load_dword v49, v[4:5], off offset:768 nt
	s_nop 0
	global_load_dword v18, v[18:19], off offset:768 nt
	s_nop 0
	global_load_dword v19, v[4:5], off nt
	v_add_u32_e32 v2, 16, v2
	v_mad_u64_u32 v[4:5], s[4:5], v21, s21, v[2:3]
	v_readlane_b32 s64, v254, 8
	v_readlane_b32 s65, v254, 9
	v_readlane_b32 s66, v254, 10
	v_readlane_b32 s67, v254, 11
	v_readlane_b32 s68, v254, 12
	v_readlane_b32 s69, v254, 13
	v_readlane_b32 s70, v254, 14
	v_readlane_b32 s71, v254, 15
	v_readlane_b32 s72, v254, 16
	v_readlane_b32 s73, v254, 17
	v_readlane_b32 s74, v254, 18
	v_readlane_b32 s75, v254, 19
	s_waitcnt vmcnt(29)
	ds_write2st64_b32 v4, v33, v35 offset1:65
	s_waitcnt vmcnt(24)
	ds_write2st64_b32 v4, v37, v6 offset0:130 offset1:195
	v_mad_u64_u32 v[4:5], s[4:5], v23, s21, v[2:3]
	ds_write2st64_b32 v4, v34, v36 offset1:65
	ds_write2st64_b32 v4, v38, v8 offset0:130 offset1:195
	v_mad_u64_u32 v[4:5], s[4:5], v25, s21, v[2:3]
	s_waitcnt vmcnt(21)
	ds_write2st64_b32 v4, v7, v39 offset1:65
	s_waitcnt vmcnt(16)
	ds_write2st64_b32 v4, v41, v10 offset0:130 offset1:195
	v_mad_u64_u32 v[4:5], s[4:5], v27, s21, v[2:3]
	ds_write2st64_b32 v4, v9, v40 offset1:65
	ds_write2st64_b32 v4, v42, v12 offset0:130 offset1:195
	v_mad_u64_u32 v[4:5], s[4:5], v28, s21, v[2:3]
	s_waitcnt vmcnt(13)
	ds_write2st64_b32 v4, v11, v43 offset1:65
	s_waitcnt vmcnt(8)
	ds_write2st64_b32 v4, v45, v14 offset0:130 offset1:195
	v_mad_u64_u32 v[4:5], s[4:5], v29, s21, v[2:3]
	ds_write2st64_b32 v4, v13, v44 offset1:65
	ds_write2st64_b32 v4, v46, v16 offset0:130 offset1:195
	v_mad_u64_u32 v[4:5], s[4:5], v30, s21, v[2:3]
	s_waitcnt vmcnt(6)
	ds_write2st64_b32 v4, v15, v17 offset1:65
	s_waitcnt vmcnt(1)
	ds_write2st64_b32 v4, v47, v18 offset0:130 offset1:195
	v_mad_u64_u32 v[4:5], s[4:5], v31, s21, v[2:3]
	v_lshlrev_b32_e32 v2, 1, v20
	v_and_b32_e32 v2, 62, v2
	v_mad_u32_u24 v10, v2, s21, 16
	s_lshl_b32 s4, s23, 1
	v_ashrrev_i32_e32 v11, 5, v20
	v_lshl_add_u32 v12, v11, 2, v10
	s_add_u32 s4, s90, s4
	s_waitcnt vmcnt(0)
	ds_write2st64_b32 v4, v19, v32 offset1:65
	ds_write2st64_b32 v4, v48, v49 offset0:130 offset1:195
	s_waitcnt lgkmcnt(0)
	s_barrier
	ds_read2_b32 v[6:7], v12 offset1:65
	s_addc_u32 s5, s91, 0
	v_lshlrev_b32_e32 v2, 1, v2
	v_lshl_add_u64 v[4:5], s[4:5], 0, v[2:3]
	s_waitcnt lgkmcnt(0)
	v_cvt_pk_bf16_f32 v2, v6, v7
	v_add_u32_e32 v6, s2, v11
	v_ashrrev_i32_e32 v7, 31, v6
	v_lshlrev_b64 v[6:7], 11, v[6:7]
	v_ashrrev_i32_e32 v13, 5, v22
	v_lshl_add_u64 v[6:7], v[4:5], 0, v[6:7]
	global_store_dword v[6:7], v2, off
	v_add_u32_e32 v6, s2, v13
	v_ashrrev_i32_e32 v7, 31, v6
	v_lshlrev_b64 v[6:7], 11, v[6:7]
	v_lshl_add_u32 v14, v13, 2, v10
	v_ashrrev_i32_e32 v15, 5, v24
	v_lshl_add_u64 v[6:7], v[4:5], 0, v[6:7]
	ds_read2_b32 v[8:9], v14 offset1:65
	s_waitcnt lgkmcnt(0)
	v_cvt_pk_bf16_f32 v2, v8, v9
	global_store_dword v[6:7], v2, off
	v_add_u32_e32 v6, s2, v15
	v_ashrrev_i32_e32 v7, 31, v6
	v_lshlrev_b64 v[6:7], 11, v[6:7]
	v_lshl_add_u32 v16, v15, 2, v10
	v_ashrrev_i32_e32 v17, 5, v26
	v_lshl_add_u64 v[6:7], v[4:5], 0, v[6:7]
	ds_read2_b32 v[8:9], v16 offset1:65
	s_waitcnt lgkmcnt(0)
	v_cvt_pk_bf16_f32 v2, v8, v9
	global_store_dword v[6:7], v2, off
	v_add_u32_e32 v6, s2, v17
	v_lshl_add_u32 v10, v17, 2, v10
	v_ashrrev_i32_e32 v7, 31, v6
	ds_read2_b32 v[8:9], v10 offset1:65
	v_lshlrev_b64 v[6:7], 11, v[6:7]
	s_waitcnt lgkmcnt(0)
	v_cvt_pk_bf16_f32 v2, v8, v9
	v_add_u32_e32 v8, 0x4000, v12
	v_lshl_add_u64 v[6:7], v[4:5], 0, v[6:7]
	s_or_b32 s4, s2, 64
	ds_read2_b32 v[8:9], v8 offset0:64 offset1:129
	global_store_dword v[6:7], v2, off
	v_add_u32_e32 v6, s4, v11
	v_add_u32_e32 v7, 0x4000, v14
	s_waitcnt lgkmcnt(0)
	v_cvt_pk_bf16_f32 v2, v8, v9
	ds_read2_b32 v[8:9], v7 offset0:64 offset1:129
	v_ashrrev_i32_e32 v7, 31, v6
	v_lshlrev_b64 v[6:7], 11, v[6:7]
	v_lshl_add_u64 v[6:7], v[4:5], 0, v[6:7]
	global_store_dword v[6:7], v2, off
	v_add_u32_e32 v6, s4, v13
	v_add_u32_e32 v7, 0x4000, v16
	s_waitcnt lgkmcnt(0)
	v_cvt_pk_bf16_f32 v2, v8, v9
	ds_read2_b32 v[8:9], v7 offset0:64 offset1:129
	v_ashrrev_i32_e32 v7, 31, v6
	v_lshlrev_b64 v[6:7], 11, v[6:7]
	v_lshl_add_u64 v[6:7], v[4:5], 0, v[6:7]
	global_store_dword v[6:7], v2, off
	v_add_u32_e32 v6, s4, v15
	v_add_u32_e32 v7, 0x4000, v10
	s_waitcnt lgkmcnt(0)
	v_cvt_pk_bf16_f32 v2, v8, v9
	ds_read2_b32 v[8:9], v7 offset0:64 offset1:129
	v_ashrrev_i32_e32 v7, 31, v6
	v_lshlrev_b64 v[6:7], 11, v[6:7]
	v_lshl_add_u64 v[6:7], v[4:5], 0, v[6:7]
	global_store_dword v[6:7], v2, off
	v_add_u32_e32 v6, s4, v17
	v_ashrrev_i32_e32 v7, 31, v6
	v_lshlrev_b64 v[6:7], 11, v[6:7]
	s_waitcnt lgkmcnt(0)
	v_cvt_pk_bf16_f32 v2, v8, v9
	v_add_u32_e32 v8, 0x8000, v12
	v_lshl_add_u64 v[6:7], v[4:5], 0, v[6:7]
	s_or_b32 s4, s2, 0x80
	ds_read2_b32 v[8:9], v8 offset0:128 offset1:193
	global_store_dword v[6:7], v2, off
	v_add_u32_e32 v6, s4, v11
	v_add_u32_e32 v7, 0x8000, v14
	s_waitcnt lgkmcnt(0)
	v_cvt_pk_bf16_f32 v2, v8, v9
	ds_read2_b32 v[8:9], v7 offset0:128 offset1:193
	v_ashrrev_i32_e32 v7, 31, v6
	v_lshlrev_b64 v[6:7], 11, v[6:7]
	v_lshl_add_u64 v[6:7], v[4:5], 0, v[6:7]
	global_store_dword v[6:7], v2, off
	v_add_u32_e32 v6, s4, v13
	v_add_u32_e32 v7, 0x8000, v16
	s_waitcnt lgkmcnt(0)
	v_cvt_pk_bf16_f32 v2, v8, v9
	ds_read2_b32 v[8:9], v7 offset0:128 offset1:193
	v_ashrrev_i32_e32 v7, 31, v6
	v_lshlrev_b64 v[6:7], 11, v[6:7]
	v_lshl_add_u64 v[6:7], v[4:5], 0, v[6:7]
	global_store_dword v[6:7], v2, off
	v_add_u32_e32 v6, s4, v15
	v_add_u32_e32 v7, 0x8000, v10
	s_waitcnt lgkmcnt(0)
	v_cvt_pk_bf16_f32 v2, v8, v9
	ds_read2_b32 v[8:9], v7 offset0:128 offset1:193
	v_ashrrev_i32_e32 v7, 31, v6
	v_lshlrev_b64 v[6:7], 11, v[6:7]
	v_lshl_add_u64 v[6:7], v[4:5], 0, v[6:7]
	global_store_dword v[6:7], v2, off
	v_add_u32_e32 v6, s4, v17
	v_ashrrev_i32_e32 v7, 31, v6
	v_lshlrev_b64 v[6:7], 11, v[6:7]
	s_waitcnt lgkmcnt(0)
	v_cvt_pk_bf16_f32 v2, v8, v9
	v_add_u32_e32 v8, 0xc200, v12
	v_lshl_add_u64 v[6:7], v[4:5], 0, v[6:7]
	s_or_b32 s2, s2, 0xc0
	ds_read2_b32 v[8:9], v8 offset0:64 offset1:129
	global_store_dword v[6:7], v2, off
	v_add_u32_e32 v6, s2, v11
	v_add_u32_e32 v7, 0xc200, v14
	s_waitcnt lgkmcnt(0)
	v_cvt_pk_bf16_f32 v2, v8, v9
	ds_read2_b32 v[8:9], v7 offset0:64 offset1:129
	v_ashrrev_i32_e32 v7, 31, v6
	v_lshlrev_b64 v[6:7], 11, v[6:7]
	v_lshl_add_u64 v[6:7], v[4:5], 0, v[6:7]
	global_store_dword v[6:7], v2, off
	v_add_u32_e32 v6, s2, v13
	v_add_u32_e32 v7, 0xc200, v16
	s_waitcnt lgkmcnt(0)
	v_cvt_pk_bf16_f32 v2, v8, v9
	ds_read2_b32 v[8:9], v7 offset0:64 offset1:129
	v_ashrrev_i32_e32 v7, 31, v6
	v_lshlrev_b64 v[6:7], 11, v[6:7]
	v_lshl_add_u64 v[6:7], v[4:5], 0, v[6:7]
	global_store_dword v[6:7], v2, off
	v_add_u32_e32 v6, s2, v15
	v_add_u32_e32 v7, 0xc200, v10
	s_waitcnt lgkmcnt(0)
	v_cvt_pk_bf16_f32 v2, v8, v9
	ds_read2_b32 v[8:9], v7 offset0:64 offset1:129
	v_ashrrev_i32_e32 v7, 31, v6
	v_lshlrev_b64 v[6:7], 11, v[6:7]
	v_lshl_add_u64 v[6:7], v[4:5], 0, v[6:7]
	global_store_dword v[6:7], v2, off
	v_add_u32_e32 v6, s2, v17
	v_ashrrev_i32_e32 v7, 31, v6
	v_readlane_b32 s64, v254, 29
	v_lshlrev_b64 v[6:7], 11, v[6:7]
	v_readlane_b32 s66, v254, 31
	v_readlane_b32 s67, v254, 32
	v_readlane_b32 s74, v254, 39
	v_readlane_b32 s75, v254, 40
	v_lshl_add_u64 v[4:5], v[4:5], 0, v[6:7]
	v_readlane_b32 s61, v254, 5
	v_readlane_b32 s65, v254, 30
	v_readlane_b32 s68, v254, 33
	v_readlane_b32 s69, v254, 34
	v_readlane_b32 s70, v254, 35
	v_readlane_b32 s71, v254, 36
	v_readlane_b32 s72, v254, 37
	v_readlane_b32 s73, v254, 38
	v_readlane_b32 s76, v254, 41
	v_readlane_b32 s77, v254, 42
	v_readlane_b32 s78, v254, 43
	v_readlane_b32 s79, v254, 44
	s_waitcnt lgkmcnt(0)
	v_cvt_pk_bf16_f32 v2, v8, v9
	global_store_dword v[4:5], v2, off
	s_barrier
	s_branch .LBB0_1803

.Lp4_cbdone:
	global_load_dwordx4 v[216:219], v152, s[76:77] nt
	global_load_dwordx4 v[220:223], v153, s[76:77] nt
	global_load_dwordx4 v[224:227], v154, s[76:77] nt
	global_load_dwordx4 v[228:231], v155, s[76:77] nt
	global_load_dwordx4 v[232:235], v156, s[76:77] nt
	global_load_dwordx4 v[236:239], v157, s[76:77] nt
	global_load_dwordx4 v[240:243], v158, s[76:77] nt
	global_load_dwordx4 v[244:247], v159, s[76:77] nt
	global_load_dwordx4 v[54:57], v152, s[76:77] offset:128 nt
	global_load_dwordx4 v[58:61], v153, s[76:77] offset:128 nt
	global_load_dwordx4 v[62:65], v154, s[76:77] offset:128 nt
	global_load_dwordx4 v[120:123], v155, s[76:77] offset:128 nt
	global_load_dwordx4 v[124:127], v156, s[76:77] offset:128 nt
	global_load_dwordx4 v[128:131], v157, s[76:77] offset:128 nt
	global_load_dwordx4 v[140:143], v158, s[76:77] offset:128 nt
	global_load_dwordx4 v[144:147], v159, s[76:77] offset:128 nt
	v_bfe_u32 v160, v150, 1, 1
	v_bfe_u32 v163, v150, 2, 1
	v_lshl_or_b32 v160, v163, 2, v160
	v_xor_b32_e32 v160, v160, v151
	v_lshlrev_b32_e32 v160, 4, v160
	v_lshl_add_u32 v160, v150, 7, v160
	v_add_u32_e32 v160, s73, v160
	v_bfe_u32 v161, v134, 1, 1
	v_bfe_u32 v163, v134, 2, 1
	v_lshl_or_b32 v161, v163, 2, v161
	v_lshlrev_b32_e32 v163, 1, v137
	v_xor_b32_e32 v161, v161, v163
	v_lshlrev_b32_e32 v161, 4, v161
	v_lshl_add_u32 v161, v134, 7, v161
	v_add_u32_e32 v161, s73, v161
	v_xor_b32_e32 v162, 16, v161
	s_waitcnt vmcnt(8)
	ds_write_b128 v160, v[216:219]
	ds_write_b128 v160, v[220:223] offset:1024
	ds_write_b128 v160, v[224:227] offset:2048
	ds_write_b128 v160, v[228:231] offset:3072
	ds_write_b128 v160, v[232:235] offset:4096
	ds_write_b128 v160, v[236:239] offset:5120
	ds_write_b128 v160, v[240:243] offset:6144
	ds_write_b128 v160, v[244:247] offset:7168
	global_load_dwordx4 v[216:219], v152, s[76:77] offset:256 nt
	global_load_dwordx4 v[220:223], v153, s[76:77] offset:256 nt
	global_load_dwordx4 v[224:227], v154, s[76:77] offset:256 nt
	global_load_dwordx4 v[228:231], v155, s[76:77] offset:256 nt
	global_load_dwordx4 v[232:235], v156, s[76:77] offset:256 nt
	global_load_dwordx4 v[236:239], v157, s[76:77] offset:256 nt
	global_load_dwordx4 v[240:243], v158, s[76:77] offset:256 nt
	global_load_dwordx4 v[244:247], v159, s[76:77] offset:256 nt
	ds_read_b128 v[184:187], v161
	ds_read_b128 v[188:191], v162
	s_waitcnt lgkmcnt(0)
	v_cvt_pk_bf16_f32 v192, v184, v185
	v_cvt_pk_bf16_f32 v193, v186, v187
	v_cvt_pk_bf16_f32 v194, v188, v189
	v_cvt_pk_bf16_f32 v195, v190, v191
	s_nop 1
	v_mfma_f32_16x16x32_bf16 v[22:25], v[192:195], v[168:171], v[22:25]
	v_mfma_f32_16x16x32_bf16 v[38:41], v[192:195], v[200:203], v[38:41]
	ds_read_b128 v[184:187], v161 offset:2048
	ds_read_b128 v[188:191], v162 offset:2048
	s_waitcnt lgkmcnt(0)
	v_cvt_pk_bf16_f32 v192, v184, v185
	v_cvt_pk_bf16_f32 v193, v186, v187
	v_cvt_pk_bf16_f32 v194, v188, v189
	v_cvt_pk_bf16_f32 v195, v190, v191
	s_nop 1
	v_mfma_f32_16x16x32_bf16 v[26:29], v[192:195], v[168:171], v[26:29]
	v_mfma_f32_16x16x32_bf16 v[42:45], v[192:195], v[200:203], v[42:45]
	ds_read_b128 v[184:187], v161 offset:4096
	ds_read_b128 v[188:191], v162 offset:4096
	s_waitcnt lgkmcnt(0)
	v_cvt_pk_bf16_f32 v192, v184, v185
	v_cvt_pk_bf16_f32 v193, v186, v187
	v_cvt_pk_bf16_f32 v194, v188, v189
	v_cvt_pk_bf16_f32 v195, v190, v191
	s_nop 1
	v_mfma_f32_16x16x32_bf16 v[30:33], v[192:195], v[168:171], v[30:33]
	v_mfma_f32_16x16x32_bf16 v[46:49], v[192:195], v[200:203], v[46:49]
	ds_read_b128 v[184:187], v161 offset:6144
	ds_read_b128 v[188:191], v162 offset:6144
	s_waitcnt lgkmcnt(0)
	v_cvt_pk_bf16_f32 v192, v184, v185
	v_cvt_pk_bf16_f32 v193, v186, v187
	v_cvt_pk_bf16_f32 v194, v188, v189
	v_cvt_pk_bf16_f32 v195, v190, v191
	s_nop 1
	v_mfma_f32_16x16x32_bf16 v[34:37], v[192:195], v[168:171], v[34:37]
	v_mfma_f32_16x16x32_bf16 v[50:53], v[192:195], v[200:203], v[50:53]
	s_waitcnt vmcnt(8)
	ds_write_b128 v160, v[54:57]
	ds_write_b128 v160, v[58:61] offset:1024
	ds_write_b128 v160, v[62:65] offset:2048
	ds_write_b128 v160, v[120:123] offset:3072
	ds_write_b128 v160, v[124:127] offset:4096
	ds_write_b128 v160, v[128:131] offset:5120
	ds_write_b128 v160, v[140:143] offset:6144
	ds_write_b128 v160, v[144:147] offset:7168
	global_load_dwordx4 v[54:57], v152, s[76:77] offset:384 nt
	global_load_dwordx4 v[58:61], v153, s[76:77] offset:384 nt
	global_load_dwordx4 v[62:65], v154, s[76:77] offset:384 nt
	global_load_dwordx4 v[120:123], v155, s[76:77] offset:384 nt
	global_load_dwordx4 v[124:127], v156, s[76:77] offset:384 nt
	global_load_dwordx4 v[128:131], v157, s[76:77] offset:384 nt
	global_load_dwordx4 v[140:143], v158, s[76:77] offset:384 nt
	global_load_dwordx4 v[144:147], v159, s[76:77] offset:384 nt
	ds_read_b128 v[184:187], v161
	ds_read_b128 v[188:191], v162
	s_waitcnt lgkmcnt(0)
	v_cvt_pk_bf16_f32 v192, v184, v185
	v_cvt_pk_bf16_f32 v193, v186, v187
	v_cvt_pk_bf16_f32 v194, v188, v189
	v_cvt_pk_bf16_f32 v195, v190, v191
	s_nop 1
	v_mfma_f32_16x16x32_bf16 v[22:25], v[192:195], v[172:175], v[22:25]
	v_mfma_f32_16x16x32_bf16 v[38:41], v[192:195], v[204:207], v[38:41]
	ds_read_b128 v[184:187], v161 offset:2048
	ds_read_b128 v[188:191], v162 offset:2048
	s_waitcnt lgkmcnt(0)
	v_cvt_pk_bf16_f32 v192, v184, v185
	v_cvt_pk_bf16_f32 v193, v186, v187
	v_cvt_pk_bf16_f32 v194, v188, v189
	v_cvt_pk_bf16_f32 v195, v190, v191
	s_nop 1
	v_mfma_f32_16x16x32_bf16 v[26:29], v[192:195], v[172:175], v[26:29]
	v_mfma_f32_16x16x32_bf16 v[42:45], v[192:195], v[204:207], v[42:45]
	ds_read_b128 v[184:187], v161 offset:4096
	ds_read_b128 v[188:191], v162 offset:4096
	s_waitcnt lgkmcnt(0)
	v_cvt_pk_bf16_f32 v192, v184, v185
	v_cvt_pk_bf16_f32 v193, v186, v187
	v_cvt_pk_bf16_f32 v194, v188, v189
	v_cvt_pk_bf16_f32 v195, v190, v191
	s_nop 1
	v_mfma_f32_16x16x32_bf16 v[30:33], v[192:195], v[172:175], v[30:33]
	v_mfma_f32_16x16x32_bf16 v[46:49], v[192:195], v[204:207], v[46:49]
	ds_read_b128 v[184:187], v161 offset:6144
	ds_read_b128 v[188:191], v162 offset:6144
	s_waitcnt lgkmcnt(0)
	v_cvt_pk_bf16_f32 v192, v184, v185
	v_cvt_pk_bf16_f32 v193, v186, v187
	v_cvt_pk_bf16_f32 v194, v188, v189
	v_cvt_pk_bf16_f32 v195, v190, v191
	s_nop 1
	v_mfma_f32_16x16x32_bf16 v[34:37], v[192:195], v[172:175], v[34:37]
	v_mfma_f32_16x16x32_bf16 v[50:53], v[192:195], v[204:207], v[50:53]
	s_waitcnt vmcnt(8)
	ds_write_b128 v160, v[216:219]
	ds_write_b128 v160, v[220:223] offset:1024
	ds_write_b128 v160, v[224:227] offset:2048
	ds_write_b128 v160, v[228:231] offset:3072
	ds_write_b128 v160, v[232:235] offset:4096
	ds_write_b128 v160, v[236:239] offset:5120
	ds_write_b128 v160, v[240:243] offset:6144
	ds_write_b128 v160, v[244:247] offset:7168
	ds_read_b128 v[184:187], v161
	ds_read_b128 v[188:191], v162
	s_waitcnt lgkmcnt(0)
	v_cvt_pk_bf16_f32 v192, v184, v185
	v_cvt_pk_bf16_f32 v193, v186, v187
	v_cvt_pk_bf16_f32 v194, v188, v189
	v_cvt_pk_bf16_f32 v195, v190, v191
	s_nop 1
	v_mfma_f32_16x16x32_bf16 v[22:25], v[192:195], v[176:179], v[22:25]
	v_mfma_f32_16x16x32_bf16 v[38:41], v[192:195], v[208:211], v[38:41]
	ds_read_b128 v[184:187], v161 offset:2048
	ds_read_b128 v[188:191], v162 offset:2048
	s_waitcnt lgkmcnt(0)
	v_cvt_pk_bf16_f32 v192, v184, v185
	v_cvt_pk_bf16_f32 v193, v186, v187
	v_cvt_pk_bf16_f32 v194, v188, v189
	v_cvt_pk_bf16_f32 v195, v190, v191
	s_nop 1
	v_mfma_f32_16x16x32_bf16 v[26:29], v[192:195], v[176:179], v[26:29]
	v_mfma_f32_16x16x32_bf16 v[42:45], v[192:195], v[208:211], v[42:45]
	ds_read_b128 v[184:187], v161 offset:4096
	ds_read_b128 v[188:191], v162 offset:4096
	s_waitcnt lgkmcnt(0)
	v_cvt_pk_bf16_f32 v192, v184, v185
	v_cvt_pk_bf16_f32 v193, v186, v187
	v_cvt_pk_bf16_f32 v194, v188, v189
	v_cvt_pk_bf16_f32 v195, v190, v191
	s_nop 1
	v_mfma_f32_16x16x32_bf16 v[30:33], v[192:195], v[176:179], v[30:33]
	v_mfma_f32_16x16x32_bf16 v[46:49], v[192:195], v[208:211], v[46:49]
	ds_read_b128 v[184:187], v161 offset:6144
	ds_read_b128 v[188:191], v162 offset:6144
	s_waitcnt lgkmcnt(0)
	v_cvt_pk_bf16_f32 v192, v184, v185
	v_cvt_pk_bf16_f32 v193, v186, v187
	v_cvt_pk_bf16_f32 v194, v188, v189
	v_cvt_pk_bf16_f32 v195, v190, v191
	s_nop 1
	v_mfma_f32_16x16x32_bf16 v[34:37], v[192:195], v[176:179], v[34:37]
	v_mfma_f32_16x16x32_bf16 v[50:53], v[192:195], v[208:211], v[50:53]
	s_waitcnt vmcnt(0)
	ds_write_b128 v160, v[54:57]
	ds_write_b128 v160, v[58:61] offset:1024
	ds_write_b128 v160, v[62:65] offset:2048
	ds_write_b128 v160, v[120:123] offset:3072
	ds_write_b128 v160, v[124:127] offset:4096
	ds_write_b128 v160, v[128:131] offset:5120
	ds_write_b128 v160, v[140:143] offset:6144
	ds_write_b128 v160, v[144:147] offset:7168
	ds_read_b128 v[184:187], v161
	ds_read_b128 v[188:191], v162
	s_waitcnt lgkmcnt(0)
	v_cvt_pk_bf16_f32 v192, v184, v185
	v_cvt_pk_bf16_f32 v193, v186, v187
	v_cvt_pk_bf16_f32 v194, v188, v189
	v_cvt_pk_bf16_f32 v195, v190, v191
	s_nop 1
	v_mfma_f32_16x16x32_bf16 v[22:25], v[192:195], v[180:183], v[22:25]
	v_mfma_f32_16x16x32_bf16 v[38:41], v[192:195], v[212:215], v[38:41]
	ds_read_b128 v[184:187], v161 offset:2048
	ds_read_b128 v[188:191], v162 offset:2048
	s_waitcnt lgkmcnt(0)
	v_cvt_pk_bf16_f32 v192, v184, v185
	v_cvt_pk_bf16_f32 v193, v186, v187
	v_cvt_pk_bf16_f32 v194, v188, v189
	v_cvt_pk_bf16_f32 v195, v190, v191
	s_nop 1
	v_mfma_f32_16x16x32_bf16 v[26:29], v[192:195], v[180:183], v[26:29]
	v_mfma_f32_16x16x32_bf16 v[42:45], v[192:195], v[212:215], v[42:45]
	ds_read_b128 v[184:187], v161 offset:4096
	ds_read_b128 v[188:191], v162 offset:4096
	s_waitcnt lgkmcnt(0)
	v_cvt_pk_bf16_f32 v192, v184, v185
	v_cvt_pk_bf16_f32 v193, v186, v187
	v_cvt_pk_bf16_f32 v194, v188, v189
	v_cvt_pk_bf16_f32 v195, v190, v191
	s_nop 1
	v_mfma_f32_16x16x32_bf16 v[30:33], v[192:195], v[180:183], v[30:33]
	v_mfma_f32_16x16x32_bf16 v[46:49], v[192:195], v[212:215], v[46:49]
	ds_read_b128 v[184:187], v161 offset:6144
	ds_read_b128 v[188:191], v162 offset:6144
	s_waitcnt lgkmcnt(0)
	v_cvt_pk_bf16_f32 v192, v184, v185
	v_cvt_pk_bf16_f32 v193, v186, v187
	v_cvt_pk_bf16_f32 v194, v188, v189
	v_cvt_pk_bf16_f32 v195, v190, v191
	s_nop 1
	v_mfma_f32_16x16x32_bf16 v[34:37], v[192:195], v[180:183], v[34:37]
	v_mfma_f32_16x16x32_bf16 v[50:53], v[192:195], v[212:215], v[50:53]
	s_nop 7
	s_nop 1
